# adds: FFN-up epilogues reuse the row statistics loaded by the first unit of the phase (panel mode: same 256 rows for all 4 units) instead of re-loading and draining vmcnt
# baseline (speedup 1.0000x reference)
.LBB0_684:
	s_add_u32 s30, s72, 0x5800000
	s_addc_u32 s31, s73, 0
	s_add_u32 s34, s72, 0x20000
	s_addc_u32 s35, s73, 0
	s_lshl_b32 s12, s15, 5
	s_mov_b64 s[36:37], 0x80
	s_and_b32 s15, s12, 0x60
	s_add_i32 m0, s33, 0x18000
	v_lshl_add_u64 v[8:9], v[8:9], 0, s[36:37]
	s_ashr_i32 s65, s92, 31
	s_ashr_i32 s66, s2, 31
	s_lshl_b32 s9, s7, 13
	s_lshl_b32 s16, s15, 7
	s_waitcnt vmcnt(2)
	s_barrier
	global_load_lds_dwordx4 v[8:9], off
	v_lshl_add_u64 v[6:7], v[6:7], 0, s[36:37]
	s_add_i32 m0, s33, 0x1a000
	s_add_i32 s67, s33, 0x8000
	s_add_i32 s74, s33, 0xa000
	global_load_lds_dwordx4 v[6:7], off
	v_lshl_add_u64 v[2:3], v[2:3], 0, s[36:37]
	s_mov_b32 m0, s67
	s_add_u32 s12, s0, 0x40080
	global_load_lds_dwordx4 v[2:3], off
	v_lshl_add_u64 v[2:3], v[4:5], 0, s[36:37]
	s_mov_b32 m0, s74
	s_addc_u32 s13, s1, 0
	global_load_lds_dwordx4 v[2:3], off
	s_add_i32 m0, s33, 0x1c000
	v_lshl_add_u64 v[2:3], s[12:13], 0, v[130:131]
	global_load_lds_dwordx4 v[2:3], off
	v_lshl_add_u64 v[2:3], s[12:13], 0, v[132:133]
	s_add_i32 m0, s33, 0x1e000
	s_cmpk_lt_u32 s14, 0x100
	global_load_lds_dwordx4 v[2:3], off
	v_lshrrev_b32_e32 v3, 1, v10
	v_and_b32_e32 v3, 24, v3
	v_and_b32_e32 v2, 15, v10
	v_lshlrev_b32_e32 v4, 1, v3
	v_lshl_or_b32 v1, s7, 6, v2
	v_lshl_or_b32 v2, v2, 6, v4
	v_lshlrev_b32_e32 v4, 2, v10
	v_and_b32_e32 v4, 32, v4
	s_waitcnt vmcnt(6)
	v_bitop3_b32 v5, v2, s9, v4 bitop3:0xde
	s_mov_b32 s75, s92
	v_bitop3_b32 v145, v2, s16, v4 bitop3:0xde
	s_mov_b32 s76, 0
	s_cselect_b64 s[38:39], -1, 0
	v_or_b32_e32 v147, s15, v3
	v_mov_b32_e32 v149, 0
	s_add_i32 s77, 0, 0x10000
	s_add_i32 s80, 0, 0x14000
	v_add_u32_e32 v151, 0, v5
	v_mov_b32_e32 v153, 0x358637bd
	s_mov_b32 s81, 0x800000
	v_mov_b64_e32 v[138:139], 0x3ff
	s_barrier
	s_mov_b32 s100, 0
	s_branch .LBB0_687

.LBB0_714:
	v_lshl_add_u32 v140, s8, 8, v1
	v_ashrrev_i32_e32 v141, 31, v140
	s_cmp_lg_u32 s100, 0
	s_cbranch_scc1 .Lup0_cached
	v_lshl_add_u64 v[142:143], v[140:141], 2, s[34:35]
	global_load_dword v144, v[142:143], off
	global_load_dword v146, v[142:143], off offset:64
	global_load_dword v148, v[142:143], off offset:128
	global_load_dword v150, v[142:143], off offset:192
	global_load_dword v152, v[142:143], off offset:512
	global_load_dword v156, v[142:143], off offset:576
	global_load_dword v157, v[142:143], off offset:640
	global_load_dword v158, v[142:143], off offset:704
	v_lshlrev_b64 v[154:155], 13, v[140:141]
	v_lshl_or_b32 v142, s6, 8, v147
	v_ashrrev_i32_e32 v143, 31, v142
	v_lshlrev_b64 v[142:143], 1, v[142:143]
	v_lshl_add_u64 v[154:155], s[30:31], 0, v[154:155]
	v_lshl_add_u64 v[154:155], v[154:155], 0, v[142:143]
	s_waitcnt vmcnt(0)
	s_cmp_eq_u64 s[78:79], 0
	s_cbranch_scc0 .Lup0_go
	v_mov_b32_e32 v238, v144
	v_mov_b32_e32 v239, v146
	v_mov_b32_e32 v240, v148
	v_mov_b32_e32 v241, v150
	v_mov_b32_e32 v242, v152
	v_mov_b32_e32 v243, v156
	v_mov_b32_e32 v244, v157
	v_mov_b32_e32 v245, v158
	s_mov_b32 s100, 1
	s_branch .Lup0_go
.Lup0_cached:
	v_lshlrev_b64 v[154:155], 13, v[140:141]
	v_lshl_or_b32 v142, s6, 8, v147
	v_ashrrev_i32_e32 v143, 31, v142
	v_lshlrev_b64 v[142:143], 1, v[142:143]
	v_lshl_add_u64 v[154:155], s[30:31], 0, v[154:155]
	v_lshl_add_u64 v[154:155], v[154:155], 0, v[142:143]
	v_mov_b32_e32 v144, v238
	v_mov_b32_e32 v146, v239
	v_mov_b32_e32 v148, v240
	v_mov_b32_e32 v150, v241
	v_mov_b32_e32 v152, v242
	v_mov_b32_e32 v156, v243
	v_mov_b32_e32 v157, v244
	v_mov_b32_e32 v158, v245
.Lup0_go:
	v_fmamk_f32 v141, v144, 0x3a800000, v153
	v_fmamk_f32 v144, v146, 0x3a800000, v153
	v_fmamk_f32 v146, v148, 0x3a800000, v153
	v_fmamk_f32 v148, v150, 0x3a800000, v153
	v_fmamk_f32 v150, v152, 0x3a800000, v153
	v_fmamk_f32 v152, v156, 0x3a800000, v153
	v_fmamk_f32 v156, v157, 0x3a800000, v153
	v_fmamk_f32 v157, v158, 0x3a800000, v153
	v_mul_f32_e32 v158, 0x4b800000, v141
	v_cmp_gt_f32_e32 vcc, s81, v141
	v_mul_f32_e32 v165, 0x4b800000, v157
	v_cmp_gt_f32_e64 s[16:17], s81, v157
	v_cndmask_b32_e32 v141, v141, v158, vcc
	v_rsq_f32_e32 v141, v141
	v_cndmask_b32_e64 v157, v157, v165, s[16:17]
	v_mul_f32_e32 v163, 0x4b800000, v152
	v_cmp_gt_f32_e64 s[12:13], s81, v152
	v_rsq_f32_e32 v157, v157
	v_mul_f32_e32 v159, 0x4b800000, v144
	v_mul_f32_e32 v164, 0x4b800000, v156
	v_cmp_gt_f32_e64 s[0:1], s81, v144
	v_cndmask_b32_e64 v152, v152, v163, s[12:13]
	v_cmp_gt_f32_e64 s[14:15], s81, v156
	v_mul_f32_e32 v161, 0x4b800000, v148
	v_cndmask_b32_e64 v144, v144, v159, s[0:1]
	v_cmp_gt_f32_e64 s[8:9], s81, v148
	v_cndmask_b32_e64 v156, v156, v164, s[14:15]
	v_rsq_f32_e32 v159, v152
	v_mul_f32_e32 v152, 0x45800000, v141
	v_cndmask_b32_e64 v148, v148, v161, s[8:9]
	v_rsq_f32_e32 v161, v156
	v_cndmask_b32_e32 v156, v141, v152, vcc
	v_pk_mul_f32 v[126:127], v[126:127], v[156:157] op_sel_hi:[1,0]
	v_pk_mul_f32 v[122:123], v[122:123], v[156:157] op_sel_hi:[1,0]
	v_rsq_f32_e32 v144, v144
	v_pk_mul_f32 v[128:129], v[128:129], v[156:157] op_sel_hi:[1,0]
	v_pk_mul_f32 v[124:125], v[124:125], v[156:157] op_sel_hi:[1,0]
	v_max_f32_e32 v122, 0, v122
	v_max_f32_e32 v127, 0, v127
	v_max_f32_e32 v126, 0, v126
	v_max_f32_e32 v123, 0, v123
	v_max_f32_e32 v128, 0, v128
	v_max_f32_e32 v124, 0, v124
	v_max_f32_e32 v129, 0, v129
	v_max_f32_e32 v125, 0, v125
	v_mul_f32_e32 v141, v122, v122
	v_mul_f32_e32 v122, v127, v127
	v_pk_mul_f32 v[114:115], v[114:115], v[156:157] op_sel_hi:[1,0]
	v_mul_f32_e32 v126, v126, v126
	v_mul_f32_e32 v127, v123, v123
	v_mul_f32_e32 v123, v128, v128
	v_mul_f32_e32 v128, v124, v124
	v_mul_f32_e32 v124, v129, v129
	v_mul_f32_e32 v125, v125, v125
	v_cvt_pk_bf16_f32 v122, v126, v122
	v_pk_mul_f32 v[118:119], v[118:119], v[156:157] op_sel_hi:[1,0]
	v_pk_mul_f32 v[116:117], v[116:117], v[156:157] op_sel_hi:[1,0]
	v_max_f32_e32 v114, 0, v114
	v_cvt_pk_bf16_f32 v123, v123, v124
	v_cvt_pk_bf16_f32 v124, v141, v127
	v_cvt_pk_bf16_f32 v125, v128, v125
	global_store_dwordx4 v[154:155], v[122:125], off
	v_pk_mul_f32 v[120:121], v[120:121], v[156:157] op_sel_hi:[1,0]
	v_max_f32_e32 v115, 0, v115
	v_mul_f32_e32 v122, v114, v114
	v_max_f32_e32 v114, 0, v119
	v_max_f32_e32 v116, 0, v116
	v_mul_f32_e32 v158, 0x45800000, v144
	v_max_f32_e32 v118, 0, v118
	v_mul_f32_e32 v114, v114, v114
	v_mul_f32_e32 v119, v115, v115
	v_max_f32_e32 v115, 0, v120
	v_mul_f32_e32 v120, v116, v116
	v_max_f32_e32 v116, 0, v121
	v_max_f32_e32 v117, 0, v117
	v_cndmask_b32_e64 v158, v144, v158, s[0:1]
	v_mul_f32_e32 v118, v118, v118
	v_mul_f32_e32 v115, v115, v115
	v_mul_f32_e32 v116, v116, v116
	v_mul_f32_e32 v117, v117, v117
	v_cvt_pk_bf16_f32 v114, v118, v114
	v_mul_f32_e32 v160, 0x4b800000, v146
	v_cmp_gt_f32_e64 s[6:7], s81, v146
	v_cvt_pk_bf16_f32 v115, v115, v116
	v_cvt_pk_bf16_f32 v116, v122, v119
	v_cvt_pk_bf16_f32 v117, v120, v117
	global_store_dwordx4 v[154:155], v[114:117], off offset:256
	v_pk_mul_f32 v[106:107], v[106:107], v[158:159] op_sel_hi:[1,0]
	v_cndmask_b32_e64 v146, v146, v160, s[6:7]
	v_or_b32_e32 v114, 16, v140
	v_ashrrev_i32_e32 v115, 31, v114
	v_pk_mul_f32 v[110:111], v[110:111], v[158:159] op_sel_hi:[1,0]
	v_pk_mul_f32 v[108:109], v[108:109], v[158:159] op_sel_hi:[1,0]
	v_max_f32_e32 v106, 0, v106
	v_rsq_f32_e32 v146, v146
	v_lshlrev_b64 v[114:115], 13, v[114:115]
	v_pk_mul_f32 v[112:113], v[112:113], v[158:159] op_sel_hi:[1,0]
	v_mul_f32_e32 v116, v106, v106
	v_max_f32_e32 v106, 0, v111
	v_max_f32_e32 v107, 0, v107
	v_max_f32_e32 v108, 0, v108
	v_lshl_add_u64 v[114:115], s[30:31], 0, v[114:115]
	v_max_f32_e32 v110, 0, v110
	v_mul_f32_e32 v106, v106, v106
	v_mul_f32_e32 v111, v107, v107
	v_max_f32_e32 v107, 0, v112
	v_mul_f32_e32 v112, v108, v108
	v_max_f32_e32 v108, 0, v113
	v_max_f32_e32 v109, 0, v109
	v_pk_mul_f32 v[98:99], v[98:99], v[158:159] op_sel_hi:[1,0]
	v_lshl_add_u64 v[114:115], v[114:115], 0, v[142:143]
	v_mul_f32_e32 v110, v110, v110
	v_mul_f32_e32 v107, v107, v107
	v_mul_f32_e32 v108, v108, v108
	v_mul_f32_e32 v109, v109, v109
	v_cvt_pk_bf16_f32 v106, v110, v106
	v_pk_mul_f32 v[102:103], v[102:103], v[158:159] op_sel_hi:[1,0]
	v_pk_mul_f32 v[100:101], v[100:101], v[158:159] op_sel_hi:[1,0]
	v_max_f32_e32 v98, 0, v98
	v_cvt_pk_bf16_f32 v107, v107, v108
	v_cvt_pk_bf16_f32 v108, v116, v111
	v_cvt_pk_bf16_f32 v109, v112, v109
	global_store_dwordx4 v[114:115], v[106:109], off
	v_pk_mul_f32 v[104:105], v[104:105], v[158:159] op_sel_hi:[1,0]
	v_max_f32_e32 v99, 0, v99
	v_mul_f32_e32 v106, v98, v98
	v_max_f32_e32 v98, 0, v103
	v_max_f32_e32 v100, 0, v100
	v_mul_f32_e32 v160, 0x45800000, v146
	v_max_f32_e32 v102, 0, v102
	v_mul_f32_e32 v98, v98, v98
	v_mul_f32_e32 v103, v99, v99
	v_max_f32_e32 v99, 0, v104
	v_mul_f32_e32 v104, v100, v100
	v_max_f32_e32 v100, 0, v105
	v_max_f32_e32 v101, 0, v101
	v_cndmask_b32_e64 v160, v146, v160, s[6:7]
	v_mul_f32_e32 v102, v102, v102
	v_mul_f32_e32 v99, v99, v99
	v_mul_f32_e32 v100, v100, v100
	v_mul_f32_e32 v101, v101, v101
	v_cvt_pk_bf16_f32 v98, v102, v98
	v_cvt_pk_bf16_f32 v99, v99, v100
	v_cvt_pk_bf16_f32 v100, v106, v103
	v_cvt_pk_bf16_f32 v101, v104, v101
	global_store_dwordx4 v[114:115], v[98:101], off offset:256
	v_pk_mul_f32 v[90:91], v[90:91], v[160:161] op_sel_hi:[1,0]
	v_pk_mul_f32 v[94:95], v[94:95], v[160:161] op_sel_hi:[1,0]
	v_or_b32_e32 v98, 32, v140
	v_ashrrev_i32_e32 v99, 31, v98
	v_pk_mul_f32 v[92:93], v[92:93], v[160:161] op_sel_hi:[1,0]
	v_max_f32_e32 v90, 0, v90
	v_rsq_f32_e32 v148, v148
	v_lshlrev_b64 v[98:99], 13, v[98:99]
	v_pk_mul_f32 v[96:97], v[96:97], v[160:161] op_sel_hi:[1,0]
	v_mul_f32_e32 v100, v90, v90
	v_max_f32_e32 v90, 0, v95
	v_max_f32_e32 v91, 0, v91
	v_max_f32_e32 v92, 0, v92
	v_lshl_add_u64 v[98:99], s[30:31], 0, v[98:99]
	v_max_f32_e32 v94, 0, v94
	v_mul_f32_e32 v90, v90, v90
	v_mul_f32_e32 v95, v91, v91
	v_max_f32_e32 v91, 0, v96
	v_mul_f32_e32 v96, v92, v92
	v_max_f32_e32 v92, 0, v97
	v_max_f32_e32 v93, 0, v93
	v_pk_mul_f32 v[82:83], v[82:83], v[160:161] op_sel_hi:[1,0]
	v_lshl_add_u64 v[98:99], v[98:99], 0, v[142:143]
	v_mul_f32_e32 v94, v94, v94
	v_mul_f32_e32 v91, v91, v91
	v_mul_f32_e32 v92, v92, v92
	v_mul_f32_e32 v93, v93, v93
	v_cvt_pk_bf16_f32 v90, v94, v90
	v_pk_mul_f32 v[86:87], v[86:87], v[160:161] op_sel_hi:[1,0]
	v_pk_mul_f32 v[84:85], v[84:85], v[160:161] op_sel_hi:[1,0]
	v_max_f32_e32 v82, 0, v82
	v_mul_f32_e32 v162, 0x4b800000, v150
	v_cmp_gt_f32_e64 s[10:11], s81, v150
	v_cvt_pk_bf16_f32 v91, v91, v92
	v_cvt_pk_bf16_f32 v92, v100, v95
	v_cvt_pk_bf16_f32 v93, v96, v93
	global_store_dwordx4 v[98:99], v[90:93], off
	v_pk_mul_f32 v[88:89], v[88:89], v[160:161] op_sel_hi:[1,0]
	v_max_f32_e32 v83, 0, v83
	v_mul_f32_e32 v90, v82, v82
	v_max_f32_e32 v82, 0, v87
	v_max_f32_e32 v84, 0, v84
	v_cndmask_b32_e64 v150, v150, v162, s[10:11]
	v_mul_f32_e32 v162, 0x45800000, v148
	v_max_f32_e32 v86, 0, v86
	v_mul_f32_e32 v82, v82, v82
	v_mul_f32_e32 v87, v83, v83
	v_max_f32_e32 v83, 0, v88
	v_mul_f32_e32 v88, v84, v84
	v_max_f32_e32 v84, 0, v89
	v_max_f32_e32 v85, 0, v85
	v_cndmask_b32_e64 v152, v148, v162, s[8:9]
	v_mul_f32_e32 v86, v86, v86
	v_mul_f32_e32 v83, v83, v83
	v_mul_f32_e32 v84, v84, v84
	v_mul_f32_e32 v85, v85, v85
	v_cvt_pk_bf16_f32 v82, v86, v82
	v_cvt_pk_bf16_f32 v83, v83, v84
	v_cvt_pk_bf16_f32 v84, v90, v87
	v_cvt_pk_bf16_f32 v85, v88, v85
	global_store_dwordx4 v[98:99], v[82:85], off offset:256
	v_pk_mul_f32 v[74:75], v[74:75], v[152:153] op_sel_hi:[1,0]
	v_pk_mul_f32 v[78:79], v[78:79], v[152:153] op_sel_hi:[1,0]
	v_or_b32_e32 v82, 48, v140
	v_ashrrev_i32_e32 v83, 31, v82
	v_pk_mul_f32 v[76:77], v[76:77], v[152:153] op_sel_hi:[1,0]
	v_max_f32_e32 v74, 0, v74
	v_rsq_f32_e32 v150, v150
	v_lshlrev_b64 v[82:83], 13, v[82:83]
	v_pk_mul_f32 v[80:81], v[80:81], v[152:153] op_sel_hi:[1,0]
	v_mul_f32_e32 v84, v74, v74
	v_max_f32_e32 v74, 0, v79
	v_max_f32_e32 v75, 0, v75
	v_max_f32_e32 v76, 0, v76
	v_lshl_add_u64 v[82:83], s[30:31], 0, v[82:83]
	v_max_f32_e32 v78, 0, v78
	v_mul_f32_e32 v74, v74, v74
	v_mul_f32_e32 v79, v75, v75
	v_max_f32_e32 v75, 0, v80
	v_mul_f32_e32 v80, v76, v76
	v_max_f32_e32 v76, 0, v81
	v_max_f32_e32 v77, 0, v77
	v_pk_mul_f32 v[66:67], v[66:67], v[152:153] op_sel_hi:[1,0]
	v_lshl_add_u64 v[82:83], v[82:83], 0, v[142:143]
	v_mul_f32_e32 v78, v78, v78
	v_mul_f32_e32 v75, v75, v75
	v_mul_f32_e32 v76, v76, v76
	v_mul_f32_e32 v77, v77, v77
	v_cvt_pk_bf16_f32 v74, v78, v74
	v_pk_mul_f32 v[70:71], v[70:71], v[152:153] op_sel_hi:[1,0]
	v_pk_mul_f32 v[68:69], v[68:69], v[152:153] op_sel_hi:[1,0]
	v_max_f32_e32 v66, 0, v66
	v_cvt_pk_bf16_f32 v75, v75, v76
	v_cvt_pk_bf16_f32 v76, v84, v79
	v_cvt_pk_bf16_f32 v77, v80, v77
	global_store_dwordx4 v[82:83], v[74:77], off
	v_pk_mul_f32 v[72:73], v[72:73], v[152:153] op_sel_hi:[1,0]
	v_max_f32_e32 v67, 0, v67
	v_mul_f32_e32 v74, v66, v66
	v_max_f32_e32 v66, 0, v71
	v_max_f32_e32 v68, 0, v68
	v_mul_f32_e32 v163, 0x45800000, v150
	v_max_f32_e32 v70, 0, v70
	v_mul_f32_e32 v66, v66, v66
	v_mul_f32_e32 v71, v67, v67
	v_max_f32_e32 v67, 0, v72
	v_mul_f32_e32 v72, v68, v68
	v_max_f32_e32 v68, 0, v73
	v_max_f32_e32 v69, 0, v69
	v_cndmask_b32_e64 v150, v150, v163, s[10:11]
	v_mul_f32_e32 v70, v70, v70
	v_mul_f32_e32 v67, v67, v67
	v_mul_f32_e32 v68, v68, v68
	v_mul_f32_e32 v69, v69, v69
	v_cvt_pk_bf16_f32 v66, v70, v66
	v_cvt_pk_bf16_f32 v67, v67, v68
	v_cvt_pk_bf16_f32 v68, v74, v71
	v_cvt_pk_bf16_f32 v69, v72, v69
	global_store_dwordx4 v[82:83], v[66:69], off offset:256
	v_pk_mul_f32 v[58:59], v[58:59], v[150:151] op_sel_hi:[1,0]
	v_pk_mul_f32 v[62:63], v[62:63], v[150:151] op_sel_hi:[1,0]
	v_add_u32_e32 v66, 0x80, v140
	v_ashrrev_i32_e32 v67, 31, v66
	v_pk_mul_f32 v[60:61], v[60:61], v[150:151] op_sel_hi:[1,0]
	v_max_f32_e32 v58, 0, v58
	v_lshlrev_b64 v[66:67], 13, v[66:67]
	v_pk_mul_f32 v[64:65], v[64:65], v[150:151] op_sel_hi:[1,0]
	v_mul_f32_e32 v68, v58, v58
	v_max_f32_e32 v58, 0, v63
	v_max_f32_e32 v59, 0, v59
	v_max_f32_e32 v60, 0, v60
	v_lshl_add_u64 v[66:67], s[30:31], 0, v[66:67]
	v_max_f32_e32 v62, 0, v62
	v_mul_f32_e32 v58, v58, v58
	v_mul_f32_e32 v63, v59, v59
	v_max_f32_e32 v59, 0, v64
	v_mul_f32_e32 v64, v60, v60
	v_max_f32_e32 v60, 0, v65
	v_max_f32_e32 v61, 0, v61
	v_pk_mul_f32 v[50:51], v[50:51], v[150:151] op_sel_hi:[1,0]
	v_lshl_add_u64 v[66:67], v[66:67], 0, v[142:143]
	v_mul_f32_e32 v62, v62, v62
	v_mul_f32_e32 v59, v59, v59
	v_mul_f32_e32 v60, v60, v60
	v_mul_f32_e32 v61, v61, v61
	v_cvt_pk_bf16_f32 v58, v62, v58
	v_pk_mul_f32 v[54:55], v[54:55], v[150:151] op_sel_hi:[1,0]
	v_pk_mul_f32 v[52:53], v[52:53], v[150:151] op_sel_hi:[1,0]
	v_max_f32_e32 v50, 0, v50
	v_cvt_pk_bf16_f32 v59, v59, v60
	v_cvt_pk_bf16_f32 v60, v68, v63
	v_cvt_pk_bf16_f32 v61, v64, v61
	global_store_dwordx4 v[66:67], v[58:61], off
	v_pk_mul_f32 v[56:57], v[56:57], v[150:151] op_sel_hi:[1,0]
	v_max_f32_e32 v51, 0, v51
	v_mul_f32_e32 v58, v50, v50
	v_max_f32_e32 v50, 0, v55
	v_max_f32_e32 v52, 0, v52
	v_mul_f32_e32 v164, 0x45800000, v159
	v_max_f32_e32 v54, 0, v54
	v_mul_f32_e32 v50, v50, v50
	v_mul_f32_e32 v55, v51, v51
	v_max_f32_e32 v51, 0, v56
	v_mul_f32_e32 v56, v52, v52
	v_max_f32_e32 v52, 0, v57
	v_max_f32_e32 v53, 0, v53
	v_cndmask_b32_e64 v148, v159, v164, s[12:13]
	v_mul_f32_e32 v54, v54, v54
	v_mul_f32_e32 v51, v51, v51
	v_mul_f32_e32 v52, v52, v52
	v_mul_f32_e32 v53, v53, v53
	v_cvt_pk_bf16_f32 v50, v54, v50
	v_cvt_pk_bf16_f32 v51, v51, v52
	v_cvt_pk_bf16_f32 v52, v58, v55
	v_cvt_pk_bf16_f32 v53, v56, v53
	global_store_dwordx4 v[66:67], v[50:53], off offset:256
	v_pk_mul_f32 v[42:43], v[42:43], v[148:149] op_sel_hi:[1,0]
	v_pk_mul_f32 v[46:47], v[46:47], v[148:149] op_sel_hi:[1,0]
	v_add_u32_e32 v50, 0x90, v140
	v_ashrrev_i32_e32 v51, 31, v50
	v_pk_mul_f32 v[44:45], v[44:45], v[148:149] op_sel_hi:[1,0]
	v_max_f32_e32 v42, 0, v42
	v_lshlrev_b64 v[50:51], 13, v[50:51]
	v_pk_mul_f32 v[48:49], v[48:49], v[148:149] op_sel_hi:[1,0]
	v_mul_f32_e32 v52, v42, v42
	v_max_f32_e32 v42, 0, v47
	v_max_f32_e32 v43, 0, v43
	v_max_f32_e32 v44, 0, v44
	v_lshl_add_u64 v[50:51], s[30:31], 0, v[50:51]
	v_max_f32_e32 v46, 0, v46
	v_mul_f32_e32 v42, v42, v42
	v_mul_f32_e32 v47, v43, v43
	v_max_f32_e32 v43, 0, v48
	v_mul_f32_e32 v48, v44, v44
	v_max_f32_e32 v44, 0, v49
	v_max_f32_e32 v45, 0, v45
	v_pk_mul_f32 v[34:35], v[34:35], v[148:149] op_sel_hi:[1,0]
	v_lshl_add_u64 v[50:51], v[50:51], 0, v[142:143]
	v_mul_f32_e32 v46, v46, v46
	v_mul_f32_e32 v43, v43, v43
	v_mul_f32_e32 v44, v44, v44
	v_mul_f32_e32 v45, v45, v45
	v_cvt_pk_bf16_f32 v42, v46, v42
	v_pk_mul_f32 v[38:39], v[38:39], v[148:149] op_sel_hi:[1,0]
	v_pk_mul_f32 v[36:37], v[36:37], v[148:149] op_sel_hi:[1,0]
	v_max_f32_e32 v34, 0, v34
	v_cvt_pk_bf16_f32 v43, v43, v44
	v_cvt_pk_bf16_f32 v44, v52, v47
	v_cvt_pk_bf16_f32 v45, v48, v45
	global_store_dwordx4 v[50:51], v[42:45], off
	v_pk_mul_f32 v[40:41], v[40:41], v[148:149] op_sel_hi:[1,0]
	v_max_f32_e32 v35, 0, v35
	v_mul_f32_e32 v42, v34, v34
	v_max_f32_e32 v34, 0, v39
	v_max_f32_e32 v36, 0, v36
	v_mul_f32_e32 v165, 0x45800000, v161
	v_max_f32_e32 v38, 0, v38
	v_mul_f32_e32 v34, v34, v34
	v_mul_f32_e32 v39, v35, v35
	v_max_f32_e32 v35, 0, v40
	v_mul_f32_e32 v40, v36, v36
	v_max_f32_e32 v36, 0, v41
	v_max_f32_e32 v37, 0, v37
	v_cndmask_b32_e64 v146, v161, v165, s[14:15]
	v_mul_f32_e32 v38, v38, v38
	v_mul_f32_e32 v35, v35, v35
	v_mul_f32_e32 v36, v36, v36
	v_mul_f32_e32 v37, v37, v37
	v_cvt_pk_bf16_f32 v34, v38, v34
	v_cvt_pk_bf16_f32 v35, v35, v36
	v_cvt_pk_bf16_f32 v36, v42, v39
	v_cvt_pk_bf16_f32 v37, v40, v37
	global_store_dwordx4 v[50:51], v[34:37], off offset:256
	v_pk_mul_f32 v[26:27], v[26:27], v[146:147] op_sel_hi:[1,0]
	v_pk_mul_f32 v[30:31], v[30:31], v[146:147] op_sel_hi:[1,0]
	v_add_u32_e32 v34, 0xa0, v140
	v_ashrrev_i32_e32 v35, 31, v34
	v_pk_mul_f32 v[28:29], v[28:29], v[146:147] op_sel_hi:[1,0]
	v_max_f32_e32 v26, 0, v26
	v_lshlrev_b64 v[34:35], 13, v[34:35]
	v_pk_mul_f32 v[32:33], v[32:33], v[146:147] op_sel_hi:[1,0]
	v_mul_f32_e32 v36, v26, v26
	v_max_f32_e32 v26, 0, v31
	v_max_f32_e32 v27, 0, v27
	v_max_f32_e32 v28, 0, v28
	v_lshl_add_u64 v[34:35], s[30:31], 0, v[34:35]
	v_max_f32_e32 v30, 0, v30
	v_mul_f32_e32 v26, v26, v26
	v_mul_f32_e32 v31, v27, v27
	v_max_f32_e32 v27, 0, v32
	v_mul_f32_e32 v32, v28, v28
	v_max_f32_e32 v28, 0, v33
	v_max_f32_e32 v29, 0, v29
	v_pk_mul_f32 v[18:19], v[18:19], v[146:147] op_sel_hi:[1,0]
	v_lshl_add_u64 v[34:35], v[34:35], 0, v[142:143]
	v_mul_f32_e32 v30, v30, v30
	v_mul_f32_e32 v27, v27, v27
	v_mul_f32_e32 v28, v28, v28
	v_mul_f32_e32 v29, v29, v29
	v_cvt_pk_bf16_f32 v26, v30, v26
	v_pk_mul_f32 v[22:23], v[22:23], v[146:147] op_sel_hi:[1,0]
	v_pk_mul_f32 v[20:21], v[20:21], v[146:147] op_sel_hi:[1,0]
	v_max_f32_e32 v18, 0, v18
	v_cvt_pk_bf16_f32 v27, v27, v28
	v_cvt_pk_bf16_f32 v28, v36, v31
	v_cvt_pk_bf16_f32 v29, v32, v29
	global_store_dwordx4 v[34:35], v[26:29], off
	v_pk_mul_f32 v[24:25], v[24:25], v[146:147] op_sel_hi:[1,0]
	v_max_f32_e32 v19, 0, v19
	v_mul_f32_e32 v26, v18, v18
	v_max_f32_e32 v18, 0, v23
	v_max_f32_e32 v20, 0, v20
	v_mul_f32_e32 v166, 0x45800000, v157
	v_max_f32_e32 v22, 0, v22
	v_mul_f32_e32 v18, v18, v18
	v_mul_f32_e32 v23, v19, v19
	v_max_f32_e32 v19, 0, v24
	v_mul_f32_e32 v24, v20, v20
	v_max_f32_e32 v20, 0, v25
	v_max_f32_e32 v21, 0, v21
	v_cndmask_b32_e64 v144, v157, v166, s[16:17]
	v_mul_f32_e32 v22, v22, v22
	v_mul_f32_e32 v19, v19, v19
	v_mul_f32_e32 v20, v20, v20
	v_mul_f32_e32 v21, v21, v21
	v_cvt_pk_bf16_f32 v18, v22, v18
	v_cvt_pk_bf16_f32 v19, v19, v20
	v_cvt_pk_bf16_f32 v20, v26, v23
	v_cvt_pk_bf16_f32 v21, v24, v21
	global_store_dwordx4 v[34:35], v[18:21], off offset:256
	v_pk_mul_f32 v[10:11], v[10:11], v[144:145] op_sel_hi:[1,0]
	v_pk_mul_f32 v[14:15], v[14:15], v[144:145] op_sel_hi:[1,0]
	v_add_u32_e32 v18, 0xb0, v140
	v_ashrrev_i32_e32 v19, 31, v18
	v_pk_mul_f32 v[12:13], v[12:13], v[144:145] op_sel_hi:[1,0]
	v_max_f32_e32 v10, 0, v10
	v_lshlrev_b64 v[18:19], 13, v[18:19]
	v_pk_mul_f32 v[16:17], v[16:17], v[144:145] op_sel_hi:[1,0]
	v_mul_f32_e32 v20, v10, v10
	v_max_f32_e32 v10, 0, v15
	v_max_f32_e32 v11, 0, v11
	v_max_f32_e32 v12, 0, v12
	v_lshl_add_u64 v[18:19], s[30:31], 0, v[18:19]
	v_max_f32_e32 v14, 0, v14
	v_mul_f32_e32 v10, v10, v10
	v_mul_f32_e32 v15, v11, v11
	v_max_f32_e32 v11, 0, v16
	v_mul_f32_e32 v16, v12, v12
	v_max_f32_e32 v12, 0, v17
	v_max_f32_e32 v13, 0, v13
	v_pk_mul_f32 v[4:5], v[4:5], v[144:145] op_sel_hi:[1,0]
	v_pk_mul_f32 v[2:3], v[2:3], v[144:145] op_sel_hi:[1,0]
	v_lshl_add_u64 v[18:19], v[18:19], 0, v[142:143]
	v_mul_f32_e32 v14, v14, v14
	v_mul_f32_e32 v11, v11, v11
	v_mul_f32_e32 v12, v12, v12
	v_mul_f32_e32 v13, v13, v13
	v_cvt_pk_bf16_f32 v10, v14, v10
	v_pk_mul_f32 v[8:9], v[8:9], v[144:145] op_sel_hi:[1,0]
	v_pk_mul_f32 v[6:7], v[6:7], v[144:145] op_sel_hi:[1,0]
	v_max_f32_e32 v2, 0, v2
	v_max_f32_e32 v3, 0, v3
	v_max_f32_e32 v4, 0, v4
	v_cvt_pk_bf16_f32 v11, v11, v12
	v_cvt_pk_bf16_f32 v12, v20, v15
	v_cvt_pk_bf16_f32 v13, v16, v13
	global_store_dwordx4 v[18:19], v[10:13], off
	v_max_f32_e32 v5, 0, v5
	v_max_f32_e32 v6, 0, v6
	v_mul_f32_e32 v10, v2, v2
	v_max_f32_e32 v2, 0, v7
	v_mul_f32_e32 v7, v3, v3
	v_max_f32_e32 v3, 0, v8
	v_mul_f32_e32 v8, v4, v4
	v_max_f32_e32 v4, 0, v9
	v_mul_f32_e32 v2, v2, v2
	v_mul_f32_e32 v3, v3, v3
	v_mul_f32_e32 v4, v4, v4
	v_mul_f32_e32 v5, v5, v5
	s_andn2_b64 vcc, exec, s[44:45]
	s_mov_b64 s[0:1], -1
	v_mul_f32_e32 v6, v6, v6
	v_cvt_pk_bf16_f32 v2, v6, v2
	v_cvt_pk_bf16_f32 v3, v3, v4
	v_cvt_pk_bf16_f32 v4, v10, v7
	v_cvt_pk_bf16_f32 v5, v8, v5
	global_store_dwordx4 v[18:19], v[2:5], off offset:256
	s_cbranch_vccnz .LBB0_686
	s_andn2_b64 vcc, exec, s[28:29]
	s_cbranch_vccnz .LBB0_685
	s_barrier
	s_branch .LBB0_685

.LBB0_1793:
	s_add_u32 s30, s72, 0x5800000
	s_addc_u32 s31, s73, 0
	s_add_u32 s34, s72, 0x60000
	s_addc_u32 s35, s73, 0
	s_lshl_b32 s12, s15, 5
	s_mov_b64 s[36:37], 0x80
	s_and_b32 s15, s12, 0x60
	s_add_i32 m0, s33, 0x18000
	v_lshl_add_u64 v[6:7], v[6:7], 0, s[36:37]
	s_lshl_b32 s9, s7, 13
	s_lshl_b32 s16, s15, 7
	s_waitcnt vmcnt(2)
	s_barrier
	global_load_lds_dwordx4 v[6:7], off
	v_lshl_add_u64 v[4:5], v[4:5], 0, s[36:37]
	s_add_i32 m0, s33, 0x1a000
	s_add_i32 s57, s33, 0x8000
	s_add_i32 s58, s33, 0xa000
	global_load_lds_dwordx4 v[4:5], off
	v_lshl_add_u64 v[0:1], v[0:1], 0, s[36:37]
	s_mov_b32 m0, s57
	s_add_u32 s12, s0, 0x40080
	global_load_lds_dwordx4 v[0:1], off
	v_lshl_add_u64 v[0:1], v[2:3], 0, s[36:37]
	s_mov_b32 m0, s58
	s_addc_u32 s13, s1, 0
	global_load_lds_dwordx4 v[0:1], off
	s_add_i32 m0, s33, 0x1c000
	v_lshl_add_u64 v[0:1], s[12:13], 0, v[128:129]
	global_load_lds_dwordx4 v[0:1], off
	v_lshl_add_u64 v[0:1], s[12:13], 0, v[130:131]
	s_add_i32 m0, s33, 0x1e000
	s_cmpk_lt_u32 s14, 0x100
	global_load_lds_dwordx4 v[0:1], off
	v_lshrrev_b32_e32 v1, 1, v8
	v_and_b32_e32 v1, 24, v1
	v_and_b32_e32 v0, 15, v8
	v_lshlrev_b32_e32 v2, 1, v1
	v_lshl_or_b32 v143, s7, 6, v0
	v_lshl_or_b32 v0, v0, 6, v2
	v_lshlrev_b32_e32 v2, 2, v8
	v_and_b32_e32 v2, 32, v2
	s_waitcnt vmcnt(6)
	v_bitop3_b32 v3, v0, s9, v2 bitop3:0xde
	v_bitop3_b32 v145, v0, s16, v2 bitop3:0xde
	s_mov_b32 s59, 0
	s_cselect_b64 s[38:39], -1, 0
	s_ashr_i32 s60, s92, 31
	s_mov_b32 s61, s92
	s_ashr_i32 s62, s2, 31
	v_or_b32_e32 v147, s15, v1
	v_mov_b32_e32 v149, 0
	s_add_i32 s63, 0, 0x10000
	s_add_i32 s64, 0, 0x14000
	v_add_u32_e32 v151, 0, v3
	v_mov_b32_e32 v152, 0x358637bd
	s_mov_b32 s65, 0x800000
	v_mov_b64_e32 v[136:137], 0x3ff
	s_barrier
	s_mov_b32 s100, 0
	s_branch .LBB0_1796

.LBB0_1823:
	v_lshl_add_u32 v138, s8, 8, v143
	v_ashrrev_i32_e32 v139, 31, v138
	s_cmp_lg_u32 s100, 0
	s_cbranch_scc1 .Lup1_cached
	v_lshl_add_u64 v[140:141], v[138:139], 2, s[34:35]
	global_load_dword v142, v[140:141], off
	global_load_dword v144, v[140:141], off offset:64
	global_load_dword v146, v[140:141], off offset:128
	global_load_dword v148, v[140:141], off offset:192
	global_load_dword v150, v[140:141], off offset:512
	global_load_dword v153, v[140:141], off offset:576
	global_load_dword v156, v[140:141], off offset:640
	global_load_dword v157, v[140:141], off offset:704
	v_lshlrev_b64 v[154:155], 13, v[138:139]
	v_lshl_or_b32 v140, s6, 8, v147
	v_ashrrev_i32_e32 v141, 31, v140
	v_lshlrev_b64 v[140:141], 1, v[140:141]
	v_lshl_add_u64 v[154:155], s[30:31], 0, v[154:155]
	v_lshl_add_u64 v[154:155], v[154:155], 0, v[140:141]
	s_waitcnt vmcnt(0)
	s_cmp_eq_u64 s[78:79], 0
	s_cbranch_scc0 .Lup1_go
	v_mov_b32_e32 v238, v142
	v_mov_b32_e32 v239, v144
	v_mov_b32_e32 v240, v146
	v_mov_b32_e32 v241, v148
	v_mov_b32_e32 v242, v150
	v_mov_b32_e32 v243, v153
	v_mov_b32_e32 v244, v156
	v_mov_b32_e32 v245, v157
	s_mov_b32 s100, 1
	s_branch .Lup1_go
.Lup1_cached:
	v_lshlrev_b64 v[154:155], 13, v[138:139]
	v_lshl_or_b32 v140, s6, 8, v147
	v_ashrrev_i32_e32 v141, 31, v140
	v_lshlrev_b64 v[140:141], 1, v[140:141]
	v_lshl_add_u64 v[154:155], s[30:31], 0, v[154:155]
	v_lshl_add_u64 v[154:155], v[154:155], 0, v[140:141]
	v_mov_b32_e32 v142, v238
	v_mov_b32_e32 v144, v239
	v_mov_b32_e32 v146, v240
	v_mov_b32_e32 v148, v241
	v_mov_b32_e32 v150, v242
	v_mov_b32_e32 v153, v243
	v_mov_b32_e32 v156, v244
	v_mov_b32_e32 v157, v245
.Lup1_go:
	v_fmamk_f32 v139, v142, 0x3a800000, v152
	v_fmamk_f32 v142, v144, 0x3a800000, v152
	v_fmamk_f32 v144, v146, 0x3a800000, v152
	v_fmamk_f32 v146, v148, 0x3a800000, v152
	v_fmamk_f32 v148, v150, 0x3a800000, v152
	v_fmamk_f32 v150, v153, 0x3a800000, v152
	v_fmamk_f32 v153, v156, 0x3a800000, v152
	v_fmamk_f32 v156, v157, 0x3a800000, v152
	v_mul_f32_e32 v157, 0x4b800000, v139
	v_cmp_gt_f32_e32 vcc, s65, v139
	v_mul_f32_e32 v162, 0x4b800000, v150
	v_cmp_gt_f32_e64 s[12:13], s65, v150
	v_cndmask_b32_e32 v139, v139, v157, vcc
	v_rsq_f32_e32 v139, v139
	v_cndmask_b32_e64 v150, v150, v162, s[12:13]
	v_rsq_f32_e32 v157, v150
	v_mul_f32_e32 v164, 0x4b800000, v156
	v_cmp_gt_f32_e64 s[16:17], s65, v156
	v_mul_f32_e32 v159, 0x4b800000, v144
	v_cmp_gt_f32_e64 s[6:7], s65, v144
	v_cndmask_b32_e64 v156, v156, v164, s[16:17]
	v_mul_f32_e32 v150, 0x45800000, v139
	v_mul_f32_e32 v158, 0x4b800000, v142
	v_cmp_gt_f32_e64 s[0:1], s65, v142
	v_cndmask_b32_e64 v144, v144, v159, s[6:7]
	v_rsq_f32_e32 v159, v156
	v_cndmask_b32_e32 v156, v139, v150, vcc
	v_cndmask_b32_e64 v142, v142, v158, s[0:1]
	v_pk_mul_f32 v[124:125], v[124:125], v[156:157] op_sel_hi:[1,0]
	v_pk_mul_f32 v[120:121], v[120:121], v[156:157] op_sel_hi:[1,0]
	v_rsq_f32_e32 v142, v142
	v_pk_mul_f32 v[126:127], v[126:127], v[156:157] op_sel_hi:[1,0]
	v_pk_mul_f32 v[122:123], v[122:123], v[156:157] op_sel_hi:[1,0]
	v_max_f32_e32 v120, 0, v120
	v_max_f32_e32 v125, 0, v125
	v_max_f32_e32 v124, 0, v124
	v_max_f32_e32 v121, 0, v121
	v_max_f32_e32 v126, 0, v126
	v_max_f32_e32 v122, 0, v122
	v_max_f32_e32 v127, 0, v127
	v_max_f32_e32 v123, 0, v123
	v_mul_f32_e32 v139, v120, v120
	v_mul_f32_e32 v120, v125, v125
	v_pk_mul_f32 v[112:113], v[112:113], v[156:157] op_sel_hi:[1,0]
	v_mul_f32_e32 v124, v124, v124
	v_mul_f32_e32 v125, v121, v121
	v_mul_f32_e32 v121, v126, v126
	v_mul_f32_e32 v126, v122, v122
	v_mul_f32_e32 v122, v127, v127
	v_mul_f32_e32 v123, v123, v123
	v_cvt_pk_bf16_f32 v120, v124, v120
	v_pk_mul_f32 v[116:117], v[116:117], v[156:157] op_sel_hi:[1,0]
	v_pk_mul_f32 v[114:115], v[114:115], v[156:157] op_sel_hi:[1,0]
	v_max_f32_e32 v112, 0, v112
	v_cvt_pk_bf16_f32 v121, v121, v122
	v_cvt_pk_bf16_f32 v122, v139, v125
	v_cvt_pk_bf16_f32 v123, v126, v123
	global_store_dwordx4 v[154:155], v[120:123], off
	v_pk_mul_f32 v[118:119], v[118:119], v[156:157] op_sel_hi:[1,0]
	v_max_f32_e32 v113, 0, v113
	v_mul_f32_e32 v120, v112, v112
	v_max_f32_e32 v112, 0, v117
	v_max_f32_e32 v114, 0, v114
	v_mul_f32_e32 v158, 0x45800000, v142
	v_max_f32_e32 v116, 0, v116
	v_mul_f32_e32 v112, v112, v112
	v_mul_f32_e32 v117, v113, v113
	v_max_f32_e32 v113, 0, v118
	v_mul_f32_e32 v118, v114, v114
	v_max_f32_e32 v114, 0, v119
	v_max_f32_e32 v115, 0, v115
	v_cndmask_b32_e64 v158, v142, v158, s[0:1]
	v_mul_f32_e32 v116, v116, v116
	v_mul_f32_e32 v113, v113, v113
	v_mul_f32_e32 v114, v114, v114
	v_mul_f32_e32 v115, v115, v115
	v_cvt_pk_bf16_f32 v112, v116, v112
	v_cvt_pk_bf16_f32 v113, v113, v114
	v_cvt_pk_bf16_f32 v114, v120, v117
	v_cvt_pk_bf16_f32 v115, v118, v115
	global_store_dwordx4 v[154:155], v[112:115], off offset:256
	v_pk_mul_f32 v[104:105], v[104:105], v[158:159] op_sel_hi:[1,0]
	v_mul_f32_e32 v160, 0x4b800000, v146
	v_or_b32_e32 v112, 16, v138
	v_cmp_gt_f32_e64 s[8:9], s65, v146
	v_ashrrev_i32_e32 v113, 31, v112
	v_pk_mul_f32 v[108:109], v[108:109], v[158:159] op_sel_hi:[1,0]
	v_pk_mul_f32 v[106:107], v[106:107], v[158:159] op_sel_hi:[1,0]
	v_max_f32_e32 v104, 0, v104
	v_cndmask_b32_e64 v146, v146, v160, s[8:9]
	v_rsq_f32_e32 v144, v144
	v_lshlrev_b64 v[112:113], 13, v[112:113]
	v_pk_mul_f32 v[110:111], v[110:111], v[158:159] op_sel_hi:[1,0]
	v_mul_f32_e32 v114, v104, v104
	v_max_f32_e32 v104, 0, v109
	v_max_f32_e32 v105, 0, v105
	v_max_f32_e32 v106, 0, v106
	v_rsq_f32_e32 v146, v146
	v_lshl_add_u64 v[112:113], s[30:31], 0, v[112:113]
	v_max_f32_e32 v108, 0, v108
	v_mul_f32_e32 v104, v104, v104
	v_mul_f32_e32 v109, v105, v105
	v_max_f32_e32 v105, 0, v110
	v_mul_f32_e32 v110, v106, v106
	v_max_f32_e32 v106, 0, v111
	v_max_f32_e32 v107, 0, v107
	v_pk_mul_f32 v[96:97], v[96:97], v[158:159] op_sel_hi:[1,0]
	v_lshl_add_u64 v[112:113], v[112:113], 0, v[140:141]
	v_mul_f32_e32 v108, v108, v108
	v_mul_f32_e32 v105, v105, v105
	v_mul_f32_e32 v106, v106, v106
	v_mul_f32_e32 v107, v107, v107
	v_cvt_pk_bf16_f32 v104, v108, v104
	v_pk_mul_f32 v[100:101], v[100:101], v[158:159] op_sel_hi:[1,0]
	v_pk_mul_f32 v[98:99], v[98:99], v[158:159] op_sel_hi:[1,0]
	v_max_f32_e32 v96, 0, v96
	v_cvt_pk_bf16_f32 v105, v105, v106
	v_cvt_pk_bf16_f32 v106, v114, v109
	v_cvt_pk_bf16_f32 v107, v110, v107
	global_store_dwordx4 v[112:113], v[104:107], off
	v_pk_mul_f32 v[102:103], v[102:103], v[158:159] op_sel_hi:[1,0]
	v_max_f32_e32 v97, 0, v97
	v_mul_f32_e32 v104, v96, v96
	v_max_f32_e32 v96, 0, v101
	v_max_f32_e32 v98, 0, v98
	v_mul_f32_e32 v161, 0x4b800000, v148
	v_cmp_gt_f32_e64 s[10:11], s65, v148
	v_mul_f32_e32 v160, 0x45800000, v144
	v_max_f32_e32 v100, 0, v100
	v_mul_f32_e32 v96, v96, v96
	v_mul_f32_e32 v101, v97, v97
	v_max_f32_e32 v97, 0, v102
	v_mul_f32_e32 v102, v98, v98
	v_max_f32_e32 v98, 0, v103
	v_max_f32_e32 v99, 0, v99
	v_cndmask_b32_e64 v148, v148, v161, s[10:11]
	v_mul_f32_e32 v161, 0x45800000, v146
	v_cndmask_b32_e64 v160, v144, v160, s[6:7]
	v_mul_f32_e32 v100, v100, v100
	v_mul_f32_e32 v97, v97, v97
	v_mul_f32_e32 v98, v98, v98
	v_mul_f32_e32 v99, v99, v99
	v_cvt_pk_bf16_f32 v96, v100, v96
	v_cvt_pk_bf16_f32 v97, v97, v98
	v_cvt_pk_bf16_f32 v98, v104, v101
	v_cvt_pk_bf16_f32 v99, v102, v99
	global_store_dwordx4 v[112:113], v[96:99], off offset:256
	v_pk_mul_f32 v[88:89], v[88:89], v[160:161] op_sel_hi:[1,0]
	v_pk_mul_f32 v[92:93], v[92:93], v[160:161] op_sel_hi:[1,0]
	v_or_b32_e32 v96, 32, v138
	v_ashrrev_i32_e32 v97, 31, v96
	v_pk_mul_f32 v[90:91], v[90:91], v[160:161] op_sel_hi:[1,0]
	v_max_f32_e32 v88, 0, v88
	v_lshlrev_b64 v[96:97], 13, v[96:97]
	v_pk_mul_f32 v[94:95], v[94:95], v[160:161] op_sel_hi:[1,0]
	v_mul_f32_e32 v98, v88, v88
	v_max_f32_e32 v88, 0, v93
	v_max_f32_e32 v89, 0, v89
	v_max_f32_e32 v90, 0, v90
	v_lshl_add_u64 v[96:97], s[30:31], 0, v[96:97]
	v_max_f32_e32 v92, 0, v92
	v_mul_f32_e32 v88, v88, v88
	v_mul_f32_e32 v93, v89, v89
	v_max_f32_e32 v89, 0, v94
	v_mul_f32_e32 v94, v90, v90
	v_max_f32_e32 v90, 0, v95
	v_max_f32_e32 v91, 0, v91
	v_pk_mul_f32 v[80:81], v[80:81], v[160:161] op_sel_hi:[1,0]
	v_lshl_add_u64 v[96:97], v[96:97], 0, v[140:141]
	v_mul_f32_e32 v92, v92, v92
	v_mul_f32_e32 v89, v89, v89
	v_mul_f32_e32 v90, v90, v90
	v_mul_f32_e32 v91, v91, v91
	v_cvt_pk_bf16_f32 v88, v92, v88
	v_pk_mul_f32 v[84:85], v[84:85], v[160:161] op_sel_hi:[1,0]
	v_pk_mul_f32 v[82:83], v[82:83], v[160:161] op_sel_hi:[1,0]
	v_max_f32_e32 v80, 0, v80
	v_cvt_pk_bf16_f32 v89, v89, v90
	v_cvt_pk_bf16_f32 v90, v98, v93
	v_cvt_pk_bf16_f32 v91, v94, v91
	global_store_dwordx4 v[96:97], v[88:91], off
	v_pk_mul_f32 v[86:87], v[86:87], v[160:161] op_sel_hi:[1,0]
	v_max_f32_e32 v81, 0, v81
	v_mul_f32_e32 v88, v80, v80
	v_max_f32_e32 v80, 0, v85
	v_max_f32_e32 v82, 0, v82
	v_max_f32_e32 v84, 0, v84
	v_mul_f32_e32 v80, v80, v80
	v_mul_f32_e32 v85, v81, v81
	v_max_f32_e32 v81, 0, v86
	v_mul_f32_e32 v86, v82, v82
	v_max_f32_e32 v82, 0, v87
	v_max_f32_e32 v83, 0, v83
	v_cndmask_b32_e64 v150, v146, v161, s[8:9]
	v_mul_f32_e32 v84, v84, v84
	v_mul_f32_e32 v81, v81, v81
	v_mul_f32_e32 v82, v82, v82
	v_mul_f32_e32 v83, v83, v83
	v_cvt_pk_bf16_f32 v80, v84, v80
	v_cvt_pk_bf16_f32 v81, v81, v82
	v_cvt_pk_bf16_f32 v82, v88, v85
	v_cvt_pk_bf16_f32 v83, v86, v83
	global_store_dwordx4 v[96:97], v[80:83], off offset:256
	v_pk_mul_f32 v[72:73], v[72:73], v[150:151] op_sel_hi:[1,0]
	v_pk_mul_f32 v[76:77], v[76:77], v[150:151] op_sel_hi:[1,0]
	v_or_b32_e32 v80, 48, v138
	v_ashrrev_i32_e32 v81, 31, v80
	v_pk_mul_f32 v[74:75], v[74:75], v[150:151] op_sel_hi:[1,0]
	v_max_f32_e32 v72, 0, v72
	v_rsq_f32_e32 v148, v148
	v_lshlrev_b64 v[80:81], 13, v[80:81]
	v_pk_mul_f32 v[78:79], v[78:79], v[150:151] op_sel_hi:[1,0]
	v_mul_f32_e32 v82, v72, v72
	v_max_f32_e32 v72, 0, v77
	v_max_f32_e32 v73, 0, v73
	v_max_f32_e32 v74, 0, v74
	v_lshl_add_u64 v[80:81], s[30:31], 0, v[80:81]
	v_max_f32_e32 v76, 0, v76
	v_mul_f32_e32 v72, v72, v72
	v_mul_f32_e32 v77, v73, v73
	v_max_f32_e32 v73, 0, v78
	v_mul_f32_e32 v78, v74, v74
	v_max_f32_e32 v74, 0, v79
	v_max_f32_e32 v75, 0, v75
	v_pk_mul_f32 v[64:65], v[64:65], v[150:151] op_sel_hi:[1,0]
	v_lshl_add_u64 v[80:81], v[80:81], 0, v[140:141]
	v_mul_f32_e32 v76, v76, v76
	v_mul_f32_e32 v73, v73, v73
	v_mul_f32_e32 v74, v74, v74
	v_mul_f32_e32 v75, v75, v75
	v_cvt_pk_bf16_f32 v72, v76, v72
	v_pk_mul_f32 v[68:69], v[68:69], v[150:151] op_sel_hi:[1,0]
	v_pk_mul_f32 v[66:67], v[66:67], v[150:151] op_sel_hi:[1,0]
	v_max_f32_e32 v64, 0, v64
	v_cvt_pk_bf16_f32 v73, v73, v74
	v_cvt_pk_bf16_f32 v74, v82, v77
	v_cvt_pk_bf16_f32 v75, v78, v75
	global_store_dwordx4 v[80:81], v[72:75], off
	v_pk_mul_f32 v[70:71], v[70:71], v[150:151] op_sel_hi:[1,0]
	v_max_f32_e32 v65, 0, v65
	v_mul_f32_e32 v72, v64, v64
	v_max_f32_e32 v64, 0, v69
	v_max_f32_e32 v66, 0, v66
	v_mul_f32_e32 v162, 0x45800000, v148
	v_max_f32_e32 v68, 0, v68
	v_mul_f32_e32 v64, v64, v64
	v_mul_f32_e32 v69, v65, v65
	v_max_f32_e32 v65, 0, v70
	v_mul_f32_e32 v70, v66, v66
	v_max_f32_e32 v66, 0, v71
	v_max_f32_e32 v67, 0, v67
	v_cndmask_b32_e64 v148, v148, v162, s[10:11]
	v_mul_f32_e32 v68, v68, v68
	v_mul_f32_e32 v65, v65, v65
	v_mul_f32_e32 v66, v66, v66
	v_mul_f32_e32 v67, v67, v67
	v_cvt_pk_bf16_f32 v64, v68, v64
	v_cvt_pk_bf16_f32 v65, v65, v66
	v_cvt_pk_bf16_f32 v66, v72, v69
	v_cvt_pk_bf16_f32 v67, v70, v67
	global_store_dwordx4 v[80:81], v[64:67], off offset:256
	v_pk_mul_f32 v[56:57], v[56:57], v[148:149] op_sel_hi:[1,0]
	v_pk_mul_f32 v[60:61], v[60:61], v[148:149] op_sel_hi:[1,0]
	v_add_u32_e32 v64, 0x80, v138
	v_ashrrev_i32_e32 v65, 31, v64
	v_pk_mul_f32 v[58:59], v[58:59], v[148:149] op_sel_hi:[1,0]
	v_max_f32_e32 v56, 0, v56
	v_lshlrev_b64 v[64:65], 13, v[64:65]
	v_pk_mul_f32 v[62:63], v[62:63], v[148:149] op_sel_hi:[1,0]
	v_mul_f32_e32 v66, v56, v56
	v_max_f32_e32 v56, 0, v61
	v_max_f32_e32 v57, 0, v57
	v_max_f32_e32 v58, 0, v58
	v_lshl_add_u64 v[64:65], s[30:31], 0, v[64:65]
	v_max_f32_e32 v60, 0, v60
	v_mul_f32_e32 v56, v56, v56
	v_mul_f32_e32 v61, v57, v57
	v_max_f32_e32 v57, 0, v62
	v_mul_f32_e32 v62, v58, v58
	v_max_f32_e32 v58, 0, v63
	v_max_f32_e32 v59, 0, v59
	v_pk_mul_f32 v[48:49], v[48:49], v[148:149] op_sel_hi:[1,0]
	v_lshl_add_u64 v[64:65], v[64:65], 0, v[140:141]
	v_mul_f32_e32 v60, v60, v60
	v_mul_f32_e32 v57, v57, v57
	v_mul_f32_e32 v58, v58, v58
	v_mul_f32_e32 v59, v59, v59
	v_cvt_pk_bf16_f32 v56, v60, v56
	v_pk_mul_f32 v[52:53], v[52:53], v[148:149] op_sel_hi:[1,0]
	v_pk_mul_f32 v[50:51], v[50:51], v[148:149] op_sel_hi:[1,0]
	v_max_f32_e32 v48, 0, v48
	v_mul_f32_e32 v163, 0x4b800000, v153
	v_cmp_gt_f32_e64 s[14:15], s65, v153
	v_cvt_pk_bf16_f32 v57, v57, v58
	v_cvt_pk_bf16_f32 v58, v66, v61
	v_cvt_pk_bf16_f32 v59, v62, v59
	global_store_dwordx4 v[64:65], v[56:59], off
	v_pk_mul_f32 v[54:55], v[54:55], v[148:149] op_sel_hi:[1,0]
	v_max_f32_e32 v49, 0, v49
	v_mul_f32_e32 v56, v48, v48
	v_max_f32_e32 v48, 0, v53
	v_max_f32_e32 v50, 0, v50
	v_cndmask_b32_e64 v153, v153, v163, s[14:15]
	v_mul_f32_e32 v163, 0x45800000, v157
	v_max_f32_e32 v52, 0, v52
	v_mul_f32_e32 v48, v48, v48
	v_mul_f32_e32 v53, v49, v49
	v_max_f32_e32 v49, 0, v54
	v_mul_f32_e32 v54, v50, v50
	v_max_f32_e32 v50, 0, v55
	v_max_f32_e32 v51, 0, v51
	v_cndmask_b32_e64 v146, v157, v163, s[12:13]
	v_mul_f32_e32 v52, v52, v52
	v_mul_f32_e32 v49, v49, v49
	v_mul_f32_e32 v50, v50, v50
	v_mul_f32_e32 v51, v51, v51
	v_cvt_pk_bf16_f32 v48, v52, v48
	v_cvt_pk_bf16_f32 v49, v49, v50
	v_cvt_pk_bf16_f32 v50, v56, v53
	v_cvt_pk_bf16_f32 v51, v54, v51
	global_store_dwordx4 v[64:65], v[48:51], off offset:256
	v_pk_mul_f32 v[40:41], v[40:41], v[146:147] op_sel_hi:[1,0]
	v_pk_mul_f32 v[44:45], v[44:45], v[146:147] op_sel_hi:[1,0]
	v_add_u32_e32 v48, 0x90, v138
	v_ashrrev_i32_e32 v49, 31, v48
	v_pk_mul_f32 v[42:43], v[42:43], v[146:147] op_sel_hi:[1,0]
	v_max_f32_e32 v40, 0, v40
	v_rsq_f32_e32 v153, v153
	v_lshlrev_b64 v[48:49], 13, v[48:49]
	v_pk_mul_f32 v[46:47], v[46:47], v[146:147] op_sel_hi:[1,0]
	v_mul_f32_e32 v50, v40, v40
	v_max_f32_e32 v40, 0, v45
	v_max_f32_e32 v41, 0, v41
	v_max_f32_e32 v42, 0, v42
	v_lshl_add_u64 v[48:49], s[30:31], 0, v[48:49]
	v_max_f32_e32 v44, 0, v44
	v_mul_f32_e32 v40, v40, v40
	v_mul_f32_e32 v45, v41, v41
	v_max_f32_e32 v41, 0, v46
	v_mul_f32_e32 v46, v42, v42
	v_max_f32_e32 v42, 0, v47
	v_max_f32_e32 v43, 0, v43
	v_pk_mul_f32 v[32:33], v[32:33], v[146:147] op_sel_hi:[1,0]
	v_lshl_add_u64 v[48:49], v[48:49], 0, v[140:141]
	v_mul_f32_e32 v44, v44, v44
	v_mul_f32_e32 v41, v41, v41
	v_mul_f32_e32 v42, v42, v42
	v_mul_f32_e32 v43, v43, v43
	v_cvt_pk_bf16_f32 v40, v44, v40
	v_pk_mul_f32 v[36:37], v[36:37], v[146:147] op_sel_hi:[1,0]
	v_pk_mul_f32 v[34:35], v[34:35], v[146:147] op_sel_hi:[1,0]
	v_max_f32_e32 v32, 0, v32
	v_cvt_pk_bf16_f32 v41, v41, v42
	v_cvt_pk_bf16_f32 v42, v50, v45
	v_cvt_pk_bf16_f32 v43, v46, v43
	global_store_dwordx4 v[48:49], v[40:43], off
	v_pk_mul_f32 v[38:39], v[38:39], v[146:147] op_sel_hi:[1,0]
	v_max_f32_e32 v33, 0, v33
	v_mul_f32_e32 v40, v32, v32
	v_max_f32_e32 v32, 0, v37
	v_max_f32_e32 v34, 0, v34
	v_mul_f32_e32 v164, 0x45800000, v153
	v_max_f32_e32 v36, 0, v36
	v_mul_f32_e32 v32, v32, v32
	v_mul_f32_e32 v37, v33, v33
	v_max_f32_e32 v33, 0, v38
	v_mul_f32_e32 v38, v34, v34
	v_max_f32_e32 v34, 0, v39
	v_max_f32_e32 v35, 0, v35
	v_cndmask_b32_e64 v144, v153, v164, s[14:15]
	v_mul_f32_e32 v36, v36, v36
	v_mul_f32_e32 v33, v33, v33
	v_mul_f32_e32 v34, v34, v34
	v_mul_f32_e32 v35, v35, v35
	v_cvt_pk_bf16_f32 v32, v36, v32
	v_cvt_pk_bf16_f32 v33, v33, v34
	v_cvt_pk_bf16_f32 v34, v40, v37
	v_cvt_pk_bf16_f32 v35, v38, v35
	global_store_dwordx4 v[48:49], v[32:35], off offset:256
	v_pk_mul_f32 v[24:25], v[24:25], v[144:145] op_sel_hi:[1,0]
	v_pk_mul_f32 v[28:29], v[28:29], v[144:145] op_sel_hi:[1,0]
	v_add_u32_e32 v32, 0xa0, v138
	v_ashrrev_i32_e32 v33, 31, v32
	v_pk_mul_f32 v[26:27], v[26:27], v[144:145] op_sel_hi:[1,0]
	v_max_f32_e32 v24, 0, v24
	v_lshlrev_b64 v[32:33], 13, v[32:33]
	v_pk_mul_f32 v[30:31], v[30:31], v[144:145] op_sel_hi:[1,0]
	v_mul_f32_e32 v34, v24, v24
	v_max_f32_e32 v24, 0, v29
	v_max_f32_e32 v25, 0, v25
	v_max_f32_e32 v26, 0, v26
	v_lshl_add_u64 v[32:33], s[30:31], 0, v[32:33]
	v_max_f32_e32 v28, 0, v28
	v_mul_f32_e32 v24, v24, v24
	v_mul_f32_e32 v29, v25, v25
	v_max_f32_e32 v25, 0, v30
	v_mul_f32_e32 v30, v26, v26
	v_max_f32_e32 v26, 0, v31
	v_max_f32_e32 v27, 0, v27
	v_pk_mul_f32 v[16:17], v[16:17], v[144:145] op_sel_hi:[1,0]
	v_lshl_add_u64 v[32:33], v[32:33], 0, v[140:141]
	v_mul_f32_e32 v28, v28, v28
	v_mul_f32_e32 v25, v25, v25
	v_mul_f32_e32 v26, v26, v26
	v_mul_f32_e32 v27, v27, v27
	v_cvt_pk_bf16_f32 v24, v28, v24
	v_pk_mul_f32 v[20:21], v[20:21], v[144:145] op_sel_hi:[1,0]
	v_pk_mul_f32 v[18:19], v[18:19], v[144:145] op_sel_hi:[1,0]
	v_max_f32_e32 v16, 0, v16
	v_cvt_pk_bf16_f32 v25, v25, v26
	v_cvt_pk_bf16_f32 v26, v34, v29
	v_cvt_pk_bf16_f32 v27, v30, v27
	global_store_dwordx4 v[32:33], v[24:27], off
	v_pk_mul_f32 v[22:23], v[22:23], v[144:145] op_sel_hi:[1,0]
	v_max_f32_e32 v17, 0, v17
	v_mul_f32_e32 v24, v16, v16
	v_max_f32_e32 v16, 0, v21
	v_max_f32_e32 v18, 0, v18
	v_mul_f32_e32 v165, 0x45800000, v159
	v_max_f32_e32 v20, 0, v20
	v_mul_f32_e32 v16, v16, v16
	v_mul_f32_e32 v21, v17, v17
	v_max_f32_e32 v17, 0, v22
	v_mul_f32_e32 v22, v18, v18
	v_max_f32_e32 v18, 0, v23
	v_max_f32_e32 v19, 0, v19
	v_cndmask_b32_e64 v142, v159, v165, s[16:17]
	v_mul_f32_e32 v20, v20, v20
	v_mul_f32_e32 v17, v17, v17
	v_mul_f32_e32 v18, v18, v18
	v_mul_f32_e32 v19, v19, v19
	v_cvt_pk_bf16_f32 v16, v20, v16
	v_cvt_pk_bf16_f32 v17, v17, v18
	v_cvt_pk_bf16_f32 v18, v24, v21
	v_cvt_pk_bf16_f32 v19, v22, v19
	global_store_dwordx4 v[32:33], v[16:19], off offset:256
	v_pk_mul_f32 v[8:9], v[8:9], v[142:143] op_sel_hi:[1,0]
	v_pk_mul_f32 v[12:13], v[12:13], v[142:143] op_sel_hi:[1,0]
	v_add_u32_e32 v16, 0xb0, v138
	v_ashrrev_i32_e32 v17, 31, v16
	v_pk_mul_f32 v[10:11], v[10:11], v[142:143] op_sel_hi:[1,0]
	v_max_f32_e32 v8, 0, v8
	v_lshlrev_b64 v[16:17], 13, v[16:17]
	v_pk_mul_f32 v[14:15], v[14:15], v[142:143] op_sel_hi:[1,0]
	v_mul_f32_e32 v18, v8, v8
	v_max_f32_e32 v8, 0, v13
	v_max_f32_e32 v9, 0, v9
	v_max_f32_e32 v10, 0, v10
	v_lshl_add_u64 v[16:17], s[30:31], 0, v[16:17]
	v_max_f32_e32 v12, 0, v12
	v_mul_f32_e32 v8, v8, v8
	v_mul_f32_e32 v13, v9, v9
	v_max_f32_e32 v9, 0, v14
	v_mul_f32_e32 v14, v10, v10
	v_max_f32_e32 v10, 0, v15
	v_max_f32_e32 v11, 0, v11
	v_pk_mul_f32 v[2:3], v[2:3], v[142:143] op_sel_hi:[1,0]
	v_pk_mul_f32 v[0:1], v[0:1], v[142:143] op_sel_hi:[1,0]
	v_lshl_add_u64 v[16:17], v[16:17], 0, v[140:141]
	v_mul_f32_e32 v12, v12, v12
	v_mul_f32_e32 v9, v9, v9
	v_mul_f32_e32 v10, v10, v10
	v_mul_f32_e32 v11, v11, v11
	v_cvt_pk_bf16_f32 v8, v12, v8
	v_pk_mul_f32 v[6:7], v[6:7], v[142:143] op_sel_hi:[1,0]
	v_pk_mul_f32 v[4:5], v[4:5], v[142:143] op_sel_hi:[1,0]
	v_max_f32_e32 v0, 0, v0
	v_max_f32_e32 v1, 0, v1
	v_max_f32_e32 v2, 0, v2
	v_cvt_pk_bf16_f32 v9, v9, v10
	v_cvt_pk_bf16_f32 v10, v18, v13
	v_cvt_pk_bf16_f32 v11, v14, v11
	global_store_dwordx4 v[16:17], v[8:11], off
	v_max_f32_e32 v3, 0, v3
	v_max_f32_e32 v4, 0, v4
	v_mul_f32_e32 v8, v0, v0
	v_max_f32_e32 v0, 0, v5
	v_mul_f32_e32 v5, v1, v1
	v_max_f32_e32 v1, 0, v6
	v_mul_f32_e32 v6, v2, v2
	v_max_f32_e32 v2, 0, v7
	v_mul_f32_e32 v0, v0, v0
	v_mul_f32_e32 v1, v1, v1
	v_mul_f32_e32 v2, v2, v2
	v_mul_f32_e32 v3, v3, v3
	s_andn2_b64 vcc, exec, s[44:45]
	s_mov_b64 s[0:1], -1
	v_mul_f32_e32 v4, v4, v4
	v_cvt_pk_bf16_f32 v0, v4, v0
	v_cvt_pk_bf16_f32 v1, v1, v2
	v_cvt_pk_bf16_f32 v2, v8, v5
	v_cvt_pk_bf16_f32 v3, v6, v3
	global_store_dwordx4 v[16:17], v[0:3], off offset:256
	s_cbranch_vccnz .LBB0_1795
	s_andn2_b64 vcc, exec, s[28:29]
	s_cbranch_vccnz .LBB0_1794
	s_barrier
	s_branch .LBB0_1794
